# ssm_pass1: unit-setup loads batched with counted waits, next-block au fragment prefetched one block ahead
# speedup vs baseline: 1.0017x; 1.0017x over previous
; __device__ __forceinline__ void ssm_unit_load(const Frame& F, int l, int g, int lane, SsmUnit& U) {
;     const int n32 = lane & 31, h = lane >> 5;
;     const float* sab = (const float*)(F.ws + WS_SAB + l * al1m(SZ_SAB)) + (size_t)g * 64 * 4;
;     const bf16_t* bb16 = (const bf16_t*)(F.ws + WS_SBB16 + l * al1m(SZ_SBB16)) + (size_t)g * 2 * 64 * 16;
; #pragma unroll
;     for (int s = 0; s < 2; ++s) { const f32x4 ab = *(const f32x4*)(sab + (n32 + 32 * s) * 4); ssm_pows(ab.x, ab.y, U.pw[s]); U.alr[s] = ab.z; U.ali[s] = ab.w;
;         U.bfr[2 * s] = *(const bf16x8*)(bb16 + (size_t)(n32 + 32 * s) * 16 + 8 * h); U.bfr[2 * s + 1] = *(const bf16x8*)(bb16 + (size_t)(64 + n32 + 32 * s) * 16 + 8 * h); }
; }
; __device__ __forceinline__ void s2_ssm_pass1(Frame& F, int l) {
;     const bf16_t* P = (const bf16_t*)(F.ws + WS_P); f32x2* E = (f32x2*)(F.ws + WS_SSME);
;     const int lane = F.lane, n32 = lane & 31, h = lane >> 5;
;     for (int u = F.gw; u < PB * 64 * SSM_NCH; u += F.ngw) {
;         const int b = u >> 11, g = (u >> 5) & 63, ch = u & 31, m0 = b * SEQ + ch * SSM_L;
;         SsmUnit U; ssm_unit_load(F, l, g, lane, U);
;         float Hr[2] = {0.f, 0.f}, Hi[2] = {0.f, 0.f}, H1r[2], H1i[2];
;         bf16x8 au = ssm_load_au(P, m0, 32, g, lane);
; #pragma unroll 1
;         for (int blk = 0; blk < SSM_L / 32; ++blk) {
;             const bf16x8 an = ssm_load_au(P, m0 + 32 * ((blk + 1) & 3), 32, g, lane);
;             f32x16 Dr[2], Di[2];
;             ssm_block32<false>(au, U, Hr, Hi, H1r, H1i, Dr, Di, h);
;             au = an;
.LBB0_423:
	s_ashr_i32 s30, s8, 11
	s_and_b32 s29, s8, 31
	s_bfe_u32 s31, s8, 0x60005
	s_lshl_b32 s4, s30, 12
	s_lshl_b32 s22, s29, 7
	s_or_b32 s34, s4, s22
	s_lshl_b32 s4, s31, 10
	s_add_u32 s24, s17, s4
	s_addc_u32 s25, s26, 0
	global_load_dwordx2 v[66:67], v118, s[24:25]
	global_load_dwordx2 v[76:77], v119, s[24:25]
	s_lshl_b32 s4, s31, 12
	s_add_u32 s22, s27, s4
	s_addc_u32 s23, s28, 0
	v_mov_b32_e32 v89, v99
	v_mov_b32_e32 v91, v99
	v_lshl_add_u64 v[132:133], s[22:23], 0, v[88:89]
	v_lshl_add_u64 v[134:135], s[22:23], 0, v[90:91]
	v_lshl_add_u64 v[132:133], v[132:133], 0, v[98:99]
	v_lshl_add_u64 v[134:135], v[134:135], 0, v[98:99]
	global_load_dwordx4 v[68:71], v[132:133], off
	global_load_dwordx4 v[72:75], v[132:133], off offset:2048
	global_load_dwordx4 v[78:81], v[134:135], off
	global_load_dwordx4 v[82:85], v[134:135], off offset:2048
	s_lshl_b32 s4, s31, 4
	v_mov_b32_e32 v114, 0
	s_lshl_b32 s4, s4, 1
	v_or_b32_e32 v138, s34, v86
	v_mov_b64_e32 v[136:137], s[54:55]
	v_mad_i64_i32 v[136:137], s[24:25], v138, s87, v[136:137]
	v_lshl_add_u64 v[136:137], v[136:137], 0, s[4:5]
	v_lshl_add_u64 v[136:137], v[136:137], 0, v[98:99]
	v_add_co_u32_e32 v136, vcc, 0xc802000, v136
	v_mov_b32_e32 v115, v114
	v_addc_co_u32_e32 v137, vcc, 0, v137, vcc
	global_load_dwordx4 v[128:131], v[136:137], off offset:3072
	v_mov_b32_e32 v116, v114
	v_mov_b32_e32 v117, v114
	s_waitcnt vmcnt(6)
	v_mul_f32_e32 v2, v67, v67
	v_pk_fma_f32 v[2:3], v[66:67], v[66:67], v[2:3] op_sel_hi:[1,1,0] neg_lo:[0,0,1] neg_hi:[0,0,1]
	v_add_f32_e32 v4, v66, v66
	v_mul_f32_e32 v5, v67, v4
	v_mov_b32_e32 v196, v2
	v_mul_f32_e32 v4, v5, v5
	v_pk_mul_f32 v[6:7], v[2:3], v[196:197] op_sel_hi:[0,1]
	v_pk_fma_f32 v[2:3], v[2:3], v[196:197], v[4:5] op_sel_hi:[0,1,1] neg_lo:[0,0,1] neg_hi:[0,0,1]
	v_pk_mul_f32 v[92:93], v[6:7], v[4:5]
	v_mov_b32_e32 v94, v2
	v_mov_b32_e32 v95, v93
	v_pk_mov_b32 v[102:103], v[66:67], v[66:67] op_sel:[1,0]
	v_mov_b32_e32 v104, v2
	v_mov_b32_e32 v105, v2
	v_pk_mov_b32 v[112:113], v[92:93], v[2:3] op_sel:[1,0]
	v_mov_b32_e32 v92, v93
	s_waitcnt vmcnt(5)
	v_mul_f32_e32 v4, v77, v77
	v_pk_fma_f32 v[4:5], v[76:77], v[76:77], v[4:5] op_sel_hi:[1,1,0] neg_lo:[0,0,1] neg_hi:[0,0,1]
	v_add_f32_e32 v6, v76, v76
	v_mul_f32_e32 v7, v77, v6
	v_mov_b32_e32 v196, v4
	v_mul_f32_e32 v6, v7, v7
	v_pk_mul_f32 v[8:9], v[4:5], v[196:197] op_sel_hi:[0,1]
	v_pk_fma_f32 v[4:5], v[4:5], v[196:197], v[6:7] op_sel_hi:[0,1,1] neg_lo:[0,0,1] neg_hi:[0,0,1]
	v_pk_mul_f32 v[96:97], v[8:9], v[6:7]
	v_mov_b32_e32 v100, v4
	v_mov_b32_e32 v101, v97
	v_pk_mov_b32 v[106:107], v[76:77], v[76:77] op_sel:[1,0]
	v_mov_b32_e32 v108, v4
	v_mov_b32_e32 v109, v4
	v_pk_mov_b32 v[110:111], v[96:97], v[4:5] op_sel:[1,0]
	v_mov_b32_e32 v96, v97
	s_mov_b32 s22, 32
	s_mov_b32 s23, s34
.LBB0_424:
	s_and_b32 s23, s22, 0x60
	s_or_b32 s23, s23, s34
	s_add_i32 s22, s22, 32
	s_waitcnt vmcnt(0)
	v_mov_b64_e32 v[18:19], v[128:129]
	v_mov_b64_e32 v[20:21], v[130:131]
	s_cmpk_eq_i32 s22, 0xa0
	s_cbranch_scc1 .Lsp1_nopf
	v_or_b32_e32 v4, s23, v86
	v_mov_b64_e32 v[2:3], s[54:55]
	v_mad_i64_i32 v[2:3], s[24:25], v4, s87, v[2:3]
	v_lshl_add_u64 v[2:3], v[2:3], 0, s[4:5]
	v_lshl_add_u64 v[2:3], v[2:3], 0, v[98:99]
	v_add_co_u32_e32 v2, vcc, 0xc802000, v2
	s_nop 0
	v_addc_co_u32_e32 v3, vcc, 0, v3, vcc
	global_load_dwordx4 v[128:131], v[2:3], off offset:3072
.Lsp1_nopf:
	s_cmpk_eq_i32 s22, 0xa0
	v_mfma_f32_32x32x16_bf16 v[50:65], v[18:21], v[72:75], 0
	s_nop 11
	v_pk_mul_f32 v[122:123], v[102:103], v[50:51] op_sel_hi:[1,0]
	v_mfma_f32_32x32x16_bf16 v[34:49], v[18:21], v[68:71], 0
	v_mfma_f32_32x32x16_bf16 v[2:17], v[18:21], v[78:81], 0
	s_nop 10
	v_fma_f32 v126, v66, v34, -v122
	v_fma_f32 v127, v67, v35, -v123
	v_fma_f32 v122, v66, v34, v122
	v_fma_f32 v123, v67, v34, v123
	v_mov_b32_e32 v50, v35
	v_mov_b32_e32 v127, v123
	v_pk_add_f32 v[34:35], v[50:51], v[126:127]
	s_nop 0
	v_pk_mul_f32 v[50:51], v[66:67], v[34:35]
	v_pk_mul_f32 v[34:35], v[102:103], v[34:35]
	v_sub_f32_e32 v50, v50, v51
	v_add_f32_e32 v34, v34, v35
	v_add_f32_e32 v34, v52, v34
	v_add_f32_e32 v36, v36, v50
	v_pk_mul_f32 v[34:35], v[102:103], v[34:35] op_sel_hi:[1,0]
	v_mov_b32_e32 v52, v37
	v_pk_fma_f32 v[50:51], v[66:67], v[36:37], v[34:35] neg_lo:[0,0,1] neg_hi:[0,0,1]
	v_pk_fma_f32 v[34:35], v[66:67], v[36:37], v[34:35] op_sel_hi:[1,0,1]
	v_mfma_f32_32x32x16_bf16 v[18:33], v[18:21], v[82:85], 0
	v_mov_b32_e32 v51, v35
	v_mul_f32_e64 v34, v102, v54
	v_mul_f32_e64 v35, v103, v54
	v_mov_b32_e32 v54, v39
	v_fma_f32 v122, v66, v38, -v34
	v_fma_f32 v123, v67, v39, -v35
	v_pk_fma_f32 v[34:35], v[66:67], v[38:39], v[34:35] op_sel_hi:[1,0,1]
	s_nop 0
	v_mov_b32_e32 v123, v35
	v_pk_add_f32 v[34:35], v[54:55], v[122:123]
	s_nop 0
	v_pk_mul_f32 v[38:39], v[66:67], v[34:35]
	v_pk_mul_f32 v[34:35], v[102:103], v[34:35]
	v_sub_f32_e32 v36, v38, v39
	v_add_f32_e32 v34, v34, v35
	v_add_f32_e32 v56, v56, v34
	v_pk_mul_f32 v[34:35], v[102:103], v[58:59] op_sel_hi:[1,0]
	v_mov_b32_e32 v58, v43
	v_pk_fma_f32 v[38:39], v[66:67], v[42:43], v[34:35] neg_lo:[0,0,1] neg_hi:[0,0,1]
	v_pk_fma_f32 v[34:35], v[66:67], v[42:43], v[34:35] op_sel_hi:[1,0,1]
	v_add_f32_e32 v54, v40, v36
	v_mov_b32_e32 v39, v35
	v_pk_add_f32 v[38:39], v[58:59], v[38:39]
	s_nop 0
	v_pk_mul_f32 v[34:35], v[66:67], v[38:39]
	v_pk_mul_f32 v[38:39], v[102:103], v[38:39]
	v_sub_f32_e32 v34, v34, v35
	v_add_f32_e32 v35, v38, v39
	v_pk_mul_f32 v[38:39], v[102:103], v[62:63] op_sel_hi:[1,0]
	v_mov_b32_e32 v62, v47
	v_pk_fma_f32 v[42:43], v[66:67], v[46:47], v[38:39] neg_lo:[0,0,1] neg_hi:[0,0,1]
	v_pk_fma_f32 v[38:39], v[66:67], v[46:47], v[38:39] op_sel_hi:[1,0,1]
	v_add_f32_e32 v36, v60, v35
	v_mov_b32_e32 v43, v39
	v_pk_add_f32 v[42:43], v[62:63], v[42:43]
	v_pk_mul_f32 v[46:47], v[102:103], v[56:57] op_sel_hi:[1,0]
	v_pk_mul_f32 v[38:39], v[66:67], v[42:43]
	v_pk_mul_f32 v[42:43], v[102:103], v[42:43]
	v_sub_f32_e32 v35, v38, v39
	v_add_f32_e32 v38, v48, v35
	v_add_f32_e32 v35, v42, v43
	v_pk_mul_f32 v[42:43], v[94:95], v[116:117]
	v_add_f32_e32 v40, v64, v35
	v_sub_f32_e32 v35, v42, v43
	v_pk_mul_f32 v[42:43], v[112:113], v[116:117]
	v_mov_b32_e32 v56, v41
	v_add_f32_e32 v39, v42, v43
	v_pk_add_f32 v[42:43], v[52:53], v[50:51]
	ds_bpermute_b32 v37, v87, v42
	ds_bpermute_b32 v41, v87, v43
	v_pk_fma_f32 v[50:51], v[66:67], v[54:55], v[46:47] neg_lo:[0,0,1] neg_hi:[0,0,1]
	v_pk_fma_f32 v[46:47], v[66:67], v[54:55], v[46:47] op_sel_hi:[1,0,1]
	v_add_f32_e32 v34, v44, v34
	v_mov_b32_e32 v51, v47
	s_waitcnt lgkmcnt(1)
; #define MFMA32(a, b, c) __builtin_amdgcn_mfma_f32_32x32x16_bf16((a), (b), (c), 0, 0, 0)
; template <bool FIX>
; __device__ __forceinline__ void ssm_block32(const bf16x8& au, const SsmUnit& U, float (&Hr)[2], float (&Hi)[2], float (&H1r)[2], float (&H1i)[2], f32x16 (&Dr)[2], f32x16 (&Di)[2], int h) {
;     f32x16 z;
; #pragma unroll
;     for (int i = 0; i < 16; ++i) z[i] = 0.f;
; #pragma unroll
;     for (int s = 0; s < 2; ++s) { Dr[s] = MFMA32(au, U.bfr[2 * s], z); Di[s] = MFMA32(au, U.bfr[2 * s + 1], z); }
; #pragma unroll
;     for (int s = 0; s < 2; ++s) {
;         const float ar = U.pw[s].r[0], ai = U.pw[s].i[0], a4r = U.pw[s].r[3], a4i = U.pw[s].i[3];
; #pragma unroll
;         for (int j = 0; j < 4; ++j)
; #pragma unroll
;             for (int e = 1; e < 4; ++e) { const int i = 4 * j + e;
;                 const float nr = ar * Dr[s][i - 1] - ai * Di[s][i - 1] + Dr[s][i], ni = ar * Di[s][i - 1] + ai * Dr[s][i - 1] + Di[s][i]; Dr[s][i] = nr; Di[s][i] = ni; }
;         float hr = Hr[s], hi = Hi[s];
; #pragma unroll
;         for (int j = 0; j < 4; ++j) {
;             const float ownr = Dr[s][4 * j + 3], owni = Di[s][4 * j + 3], othr = __shfl_xor(ownr, 32), othi = __shfl_xor(owni, 32);
;             const float evr = h ? othr : ownr, evi = h ? othi : owni, odr = h ? ownr : othr, odi = h ? owni : othi;
;             const float inr0 = hr, ini0 = hi;
;             float t = a4r * hr - a4i * hi + evr; hi = a4r * hi + a4i * hr + evi; hr = t;
;             if (j == 0) { H1r[s] = hr; H1i[s] = hi; }
;             const float inr1 = hr, ini1 = hi;
;             t = a4r * hr - a4i * hi + odr; hi = a4r * hi + a4i * hr + odi; hr = t;
;             if (FIX) { const float inr = h ? inr1 : inr0, ini = h ? ini1 : ini0;
; #pragma unroll
;                 for (int e = 0; e < 4; ++e) { const int i = 4 * j + e; Dr[s][i] += U.pw[s].r[e] * inr - U.pw[s].i[e] * ini; Di[s][i] += U.pw[s].r[e] * ini + U.pw[s].i[e] * inr; } }
;         }
;         Hr[s] = hr; Hi[s] = hi;
;     }
	v_cndmask_b32_e64 v44, v37, v42, s[40:41]
	s_waitcnt lgkmcnt(0)
	v_cndmask_b32_e64 v48, v41, v43, s[40:41]
	v_pk_add_f32 v[46:47], v[56:57], v[50:51]
	v_add_f32_e32 v51, v35, v44
	v_add_f32_e32 v50, v39, v48
	v_pk_mul_f32 v[52:53], v[104:105], v[50:51]
	v_cndmask_b32_e64 v42, v42, v37, s[40:41]
	ds_bpermute_b32 v35, v87, v46
	ds_bpermute_b32 v37, v87, v47
	v_pk_fma_f32 v[54:55], v[92:93], v[50:51], v[52:53] op_sel:[0,0,1] op_sel_hi:[1,1,0] neg_lo:[1,0,0] neg_hi:[1,0,0]
	v_pk_fma_f32 v[50:51], v[92:93], v[50:51], v[52:53] op_sel:[0,0,1] op_sel_hi:[1,1,0]
	v_cndmask_b32_e64 v43, v43, v41, s[40:41]
	v_mov_b32_e32 v55, v51
	v_pk_add_f32 v[42:43], v[42:43], v[54:55]
	v_mov_b32_e32 v60, v45
	v_pk_mul_f32 v[50:51], v[92:93], v[42:43]
	v_mov_b32_e32 v64, v49
	v_pk_fma_f32 v[52:53], v[104:105], v[42:43], v[50:51] op_sel:[0,0,1] op_sel_hi:[1,1,0] neg_lo:[0,0,1] neg_hi:[0,0,1]
	v_pk_fma_f32 v[42:43], v[104:105], v[42:43], v[50:51] op_sel:[0,0,1] op_sel_hi:[1,1,0]
	s_nop 0
	v_mov_b32_e32 v53, v43
	s_waitcnt lgkmcnt(0)
	v_cndmask_b32_e64 v43, v37, v47, s[40:41]
	v_cndmask_b32_e64 v42, v35, v46, s[40:41]
	v_pk_add_f32 v[42:43], v[42:43], v[52:53]
	v_cndmask_b32_e64 v47, v47, v37, s[40:41]
	v_pk_mul_f32 v[50:51], v[92:93], v[42:43]
	v_cndmask_b32_e64 v46, v46, v35, s[40:41]
	v_pk_fma_f32 v[52:53], v[104:105], v[42:43], v[50:51] op_sel:[0,0,1] op_sel_hi:[1,1,0] neg_lo:[0,0,1] neg_hi:[0,0,1]
	v_pk_fma_f32 v[42:43], v[104:105], v[42:43], v[50:51] op_sel:[0,0,1] op_sel_hi:[1,1,0]
	v_pk_mul_f32 v[36:37], v[102:103], v[36:37] op_sel_hi:[1,0]
	v_mov_b32_e32 v53, v43
	v_pk_add_f32 v[42:43], v[46:47], v[52:53]
	s_nop 0
	v_pk_mul_f32 v[46:47], v[92:93], v[42:43]
	s_nop 0
	v_pk_fma_f32 v[50:51], v[104:105], v[42:43], v[46:47] op_sel:[0,0,1] op_sel_hi:[1,1,0] neg_lo:[0,0,1] neg_hi:[0,0,1]
	v_pk_fma_f32 v[42:43], v[104:105], v[42:43], v[46:47] op_sel:[0,0,1] op_sel_hi:[1,1,0]
	s_nop 0
	v_mov_b32_e32 v51, v43
	v_pk_fma_f32 v[42:43], v[66:67], v[34:35], v[36:37] neg_lo:[0,0,1] neg_hi:[0,0,1]
	v_pk_fma_f32 v[34:35], v[66:67], v[34:35], v[36:37] op_sel_hi:[1,0,1]
	v_pk_mul_f32 v[36:37], v[102:103], v[40:41] op_sel_hi:[1,0]
	v_mov_b32_e32 v43, v35
	v_pk_fma_f32 v[40:41], v[66:67], v[38:39], v[36:37] neg_lo:[0,0,1] neg_hi:[0,0,1]
	v_pk_fma_f32 v[36:37], v[66:67], v[38:39], v[36:37] op_sel_hi:[1,0,1]
	v_pk_add_f32 v[34:35], v[60:61], v[42:43]
	v_mov_b32_e32 v41, v37
	v_pk_add_f32 v[36:37], v[64:65], v[40:41]
	ds_bpermute_b32 v40, v87, v34
	ds_bpermute_b32 v41, v87, v35
	ds_bpermute_b32 v44, v87, v36
	ds_bpermute_b32 v45, v87, v37
	s_waitcnt lgkmcnt(3)
	v_cndmask_b32_e64 v38, v40, v34, s[40:41]
	s_waitcnt lgkmcnt(2)
	v_cndmask_b32_e64 v39, v41, v35, s[40:41]
	v_pk_add_f32 v[38:39], v[38:39], v[50:51]
	v_cndmask_b32_e64 v35, v35, v41, s[40:41]
	v_cndmask_b32_e64 v34, v34, v40, s[40:41]
	v_pk_mul_f32 v[40:41], v[92:93], v[38:39] op_sel:[0,1] op_sel_hi:[1,0]
	s_nop 0
	v_pk_fma_f32 v[42:43], v[104:105], v[38:39], v[40:41] neg_lo:[0,0,1] neg_hi:[0,0,1]
	v_pk_fma_f32 v[38:39], v[104:105], v[38:39], v[40:41]
	s_nop 0
	v_mov_b32_e32 v43, v39
	v_pk_add_f32 v[34:35], v[34:35], v[42:43]
	s_nop 0
	v_pk_mul_f32 v[38:39], v[92:93], v[34:35]
	s_nop 0
	v_pk_fma_f32 v[40:41], v[104:105], v[34:35], v[38:39] op_sel:[0,0,1] op_sel_hi:[1,1,0] neg_lo:[0,0,1] neg_hi:[0,0,1]
	v_pk_fma_f32 v[34:35], v[104:105], v[34:35], v[38:39] op_sel:[0,0,1] op_sel_hi:[1,1,0]
	s_nop 0
	v_mov_b32_e32 v41, v35
	s_waitcnt lgkmcnt(0)
	v_cndmask_b32_e64 v35, v45, v37, s[40:41]
	v_cndmask_b32_e64 v34, v44, v36, s[40:41]
	v_pk_add_f32 v[34:35], v[34:35], v[40:41]
	v_cndmask_b32_e64 v37, v37, v45, s[40:41]
	v_pk_mul_f32 v[38:39], v[92:93], v[34:35]
	v_cndmask_b32_e64 v36, v36, v44, s[40:41]
	v_pk_fma_f32 v[40:41], v[104:105], v[34:35], v[38:39] op_sel:[0,0,1] op_sel_hi:[1,1,0] neg_lo:[0,0,1] neg_hi:[0,0,1]
	v_pk_fma_f32 v[34:35], v[104:105], v[34:35], v[38:39] op_sel:[0,0,1] op_sel_hi:[1,1,0]
	s_nop 0
	v_mov_b32_e32 v41, v35
	v_pk_mul_f32 v[34:35], v[106:107], v[18:19] op_sel_hi:[1,0]
	v_pk_add_f32 v[116:117], v[36:37], v[40:41]
	v_pk_fma_f32 v[36:37], v[76:77], v[2:3], v[34:35] neg_lo:[0,0,1] neg_hi:[0,0,1]
	v_pk_fma_f32 v[34:35], v[76:77], v[2:3], v[34:35] op_sel_hi:[1,0,1]
	v_mov_b32_e32 v18, v3
	v_mov_b32_e32 v37, v35
	v_pk_add_f32 v[2:3], v[18:19], v[36:37]
	s_nop 0
	v_pk_mul_f32 v[18:19], v[76:77], v[2:3]
	v_pk_mul_f32 v[2:3], v[106:107], v[2:3]
	v_sub_f32_e32 v18, v18, v19
	v_add_f32_e32 v2, v2, v3
	v_add_f32_e32 v2, v20, v2
	v_add_f32_e32 v4, v4, v18
	v_pk_mul_f32 v[2:3], v[106:107], v[2:3] op_sel_hi:[1,0]
	v_mov_b32_e32 v20, v5
	v_pk_fma_f32 v[18:19], v[76:77], v[4:5], v[2:3] neg_lo:[0,0,1] neg_hi:[0,0,1]
	v_pk_fma_f32 v[2:3], v[76:77], v[4:5], v[2:3] op_sel_hi:[1,0,1]
	s_nop 0
	v_mov_b32_e32 v19, v3
	v_pk_mul_f32 v[2:3], v[106:107], v[22:23] op_sel_hi:[1,0]
	v_mov_b32_e32 v22, v7
	v_pk_fma_f32 v[34:35], v[76:77], v[6:7], v[2:3] neg_lo:[0,0,1] neg_hi:[0,0,1]
	v_pk_fma_f32 v[2:3], v[76:77], v[6:7], v[2:3] op_sel_hi:[1,0,1]
	s_nop 0
	v_mov_b32_e32 v35, v3
	v_pk_add_f32 v[2:3], v[22:23], v[34:35]
	s_nop 0
	v_pk_mul_f32 v[6:7], v[76:77], v[2:3]
	v_pk_mul_f32 v[2:3], v[106:107], v[2:3]
	v_sub_f32_e32 v4, v6, v7
	v_add_f32_e32 v2, v2, v3
	v_add_f32_e32 v24, v24, v2
	v_pk_mul_f32 v[2:3], v[106:107], v[26:27] op_sel_hi:[1,0]
	v_mov_b32_e32 v26, v11
	v_pk_fma_f32 v[6:7], v[76:77], v[10:11], v[2:3] neg_lo:[0,0,1] neg_hi:[0,0,1]
	v_pk_fma_f32 v[2:3], v[76:77], v[10:11], v[2:3] op_sel_hi:[1,0,1]
	v_add_f32_e32 v22, v8, v4
	v_mov_b32_e32 v7, v3
	v_pk_add_f32 v[6:7], v[26:27], v[6:7]
	s_nop 0
	v_pk_mul_f32 v[2:3], v[76:77], v[6:7]
	v_pk_mul_f32 v[6:7], v[106:107], v[6:7]
	v_sub_f32_e32 v2, v2, v3
	v_add_f32_e32 v3, v6, v7
	v_pk_mul_f32 v[6:7], v[106:107], v[30:31] op_sel_hi:[1,0]
	v_mov_b32_e32 v30, v15
	v_pk_fma_f32 v[10:11], v[76:77], v[14:15], v[6:7] neg_lo:[0,0,1] neg_hi:[0,0,1]
	v_pk_fma_f32 v[6:7], v[76:77], v[14:15], v[6:7] op_sel_hi:[1,0,1]
	v_add_f32_e32 v4, v28, v3
	v_mov_b32_e32 v11, v7
	v_pk_add_f32 v[10:11], v[30:31], v[10:11]
	v_pk_mul_f32 v[14:15], v[106:107], v[24:25] op_sel_hi:[1,0]
	v_pk_mul_f32 v[6:7], v[76:77], v[10:11]
	v_pk_mul_f32 v[10:11], v[106:107], v[10:11]
	v_sub_f32_e32 v3, v6, v7
	v_add_f32_e32 v6, v16, v3
	v_add_f32_e32 v3, v10, v11
	v_pk_mul_f32 v[10:11], v[100:101], v[114:115]
	v_add_f32_e32 v8, v32, v3
	v_sub_f32_e32 v3, v10, v11
	v_pk_mul_f32 v[10:11], v[110:111], v[114:115]
	v_mov_b32_e32 v24, v9
	v_add_f32_e32 v7, v10, v11
	v_pk_add_f32 v[10:11], v[20:21], v[18:19]
	ds_bpermute_b32 v5, v87, v10
	ds_bpermute_b32 v9, v87, v11
	v_pk_fma_f32 v[18:19], v[76:77], v[22:23], v[14:15] neg_lo:[0,0,1] neg_hi:[0,0,1]
	v_pk_fma_f32 v[14:15], v[76:77], v[22:23], v[14:15] op_sel_hi:[1,0,1]
	v_add_f32_e32 v2, v12, v2
	v_mov_b32_e32 v19, v15
	s_waitcnt lgkmcnt(1)
; template <bool FIX>
; __device__ __forceinline__ void ssm_block32(const bf16x8& au, const SsmUnit& U, float (&Hr)[2], float (&Hi)[2], float (&H1r)[2], float (&H1i)[2], f32x16 (&Dr)[2], f32x16 (&Di)[2], int h) {
;     ...
;         float hr = Hr[s], hi = Hi[s];
; #pragma unroll
;         for (int j = 0; j < 4; ++j) {
;             const float ownr = Dr[s][4 * j + 3], owni = Di[s][4 * j + 3], othr = __shfl_xor(ownr, 32), othi = __shfl_xor(owni, 32);
;             const float evr = h ? othr : ownr, evi = h ? othi : owni, odr = h ? ownr : othr, odi = h ? owni : othi;
;             const float inr0 = hr, ini0 = hi;
;             float t = a4r * hr - a4i * hi + evr; hi = a4r * hi + a4i * hr + evi; hr = t;
;             if (j == 0) { H1r[s] = hr; H1i[s] = hi; }
;             const float inr1 = hr, ini1 = hi;
;             t = a4r * hr - a4i * hi + odr; hi = a4r * hi + a4i * hr + odi; hr = t;
;             if (FIX) { const float inr = h ? inr1 : inr0, ini = h ? ini1 : ini0;
; #pragma unroll
;                 for (int e = 0; e < 4; ++e) { const int i = 4 * j + e; Dr[s][i] += U.pw[s].r[e] * inr - U.pw[s].i[e] * ini; Di[s][i] += U.pw[s].r[e] * ini + U.pw[s].i[e] * inr; } }
;         }
;         Hr[s] = hr; Hi[s] = hi;
;     }
; __device__ __forceinline__ void s2_ssm_pass1(Frame& F, int l) {
;     ...
;         for (int blk = 0; blk < SSM_L / 32; ++blk) {
;             const bf16x8 an = ssm_load_au(P, m0 + 32 * ((blk + 1) & 3), 32, g, lane);
;             f32x16 Dr[2], Di[2];
;             ssm_block32<false>(au, U, Hr, Hi, H1r, H1i, Dr, Di, h);
;             au = an;
;         }
;         if (h == 0) { f32x2* e = E + ((size_t)(b * 64 + g) * SSM_NCH + ch) * 64; e[n32] = (f32x2){Hr[0], Hi[0]}; e[32 + n32] = (f32x2){Hr[1], Hi[1]}; }
	v_cndmask_b32_e64 v12, v5, v10, s[40:41]
	s_waitcnt lgkmcnt(0)
	v_cndmask_b32_e64 v16, v9, v11, s[40:41]
	v_pk_add_f32 v[14:15], v[24:25], v[18:19]
	v_add_f32_e32 v19, v3, v12
	v_add_f32_e32 v18, v7, v16
	v_pk_mul_f32 v[20:21], v[108:109], v[18:19]
	ds_bpermute_b32 v3, v87, v14
	ds_bpermute_b32 v7, v87, v15
	v_pk_fma_f32 v[22:23], v[96:97], v[18:19], v[20:21] op_sel:[0,0,1] op_sel_hi:[1,1,0] neg_lo:[1,0,0] neg_hi:[1,0,0]
	v_pk_fma_f32 v[18:19], v[96:97], v[18:19], v[20:21] op_sel:[0,0,1] op_sel_hi:[1,1,0]
	v_cndmask_b32_e64 v11, v11, v9, s[40:41]
	v_cndmask_b32_e64 v10, v10, v5, s[40:41]
	v_mov_b32_e32 v23, v19
	v_pk_add_f32 v[10:11], v[10:11], v[22:23]
	v_pk_mul_f32 v[4:5], v[106:107], v[4:5] op_sel_hi:[1,0]
	v_pk_mul_f32 v[18:19], v[96:97], v[10:11]
	v_mov_b32_e32 v28, v13
	v_pk_fma_f32 v[20:21], v[108:109], v[10:11], v[18:19] op_sel:[0,0,1] op_sel_hi:[1,1,0] neg_lo:[0,0,1] neg_hi:[0,0,1]
	v_pk_fma_f32 v[10:11], v[108:109], v[10:11], v[18:19] op_sel:[0,0,1] op_sel_hi:[1,1,0]
	v_mov_b32_e32 v32, v17
	v_mov_b32_e32 v21, v11
	s_waitcnt lgkmcnt(0)
	v_cndmask_b32_e64 v11, v7, v15, s[40:41]
	v_cndmask_b32_e64 v10, v3, v14, s[40:41]
	v_pk_add_f32 v[10:11], v[10:11], v[20:21]
	v_cndmask_b32_e64 v15, v15, v7, s[40:41]
	v_pk_mul_f32 v[18:19], v[96:97], v[10:11]
	v_cndmask_b32_e64 v14, v14, v3, s[40:41]
	v_pk_fma_f32 v[20:21], v[108:109], v[10:11], v[18:19] op_sel:[0,0,1] op_sel_hi:[1,1,0] neg_lo:[0,0,1] neg_hi:[0,0,1]
	v_pk_fma_f32 v[10:11], v[108:109], v[10:11], v[18:19] op_sel:[0,0,1] op_sel_hi:[1,1,0]
	s_nop 0
	v_mov_b32_e32 v21, v11
	v_pk_add_f32 v[10:11], v[14:15], v[20:21]
	s_nop 0
	v_pk_mul_f32 v[14:15], v[96:97], v[10:11]
	s_nop 0
	v_pk_fma_f32 v[18:19], v[108:109], v[10:11], v[14:15] op_sel:[0,0,1] op_sel_hi:[1,1,0] neg_lo:[0,0,1] neg_hi:[0,0,1]
	v_pk_fma_f32 v[10:11], v[108:109], v[10:11], v[14:15] op_sel:[0,0,1] op_sel_hi:[1,1,0]
	s_nop 0
	v_mov_b32_e32 v19, v11
	v_pk_fma_f32 v[10:11], v[76:77], v[2:3], v[4:5] neg_lo:[0,0,1] neg_hi:[0,0,1]
	v_pk_fma_f32 v[2:3], v[76:77], v[2:3], v[4:5] op_sel_hi:[1,0,1]
	v_pk_mul_f32 v[4:5], v[106:107], v[8:9] op_sel_hi:[1,0]
	v_mov_b32_e32 v11, v3
	v_pk_fma_f32 v[8:9], v[76:77], v[6:7], v[4:5] neg_lo:[0,0,1] neg_hi:[0,0,1]
	v_pk_fma_f32 v[4:5], v[76:77], v[6:7], v[4:5] op_sel_hi:[1,0,1]
	v_pk_add_f32 v[2:3], v[28:29], v[10:11]
	v_mov_b32_e32 v9, v5
	v_pk_add_f32 v[4:5], v[32:33], v[8:9]
	ds_bpermute_b32 v8, v87, v2
	ds_bpermute_b32 v9, v87, v3
	ds_bpermute_b32 v12, v87, v4
	ds_bpermute_b32 v13, v87, v5
	s_waitcnt lgkmcnt(3)
	v_cndmask_b32_e64 v6, v8, v2, s[40:41]
	s_waitcnt lgkmcnt(2)
	v_cndmask_b32_e64 v7, v9, v3, s[40:41]
	v_pk_add_f32 v[6:7], v[6:7], v[18:19]
	v_cndmask_b32_e64 v3, v3, v9, s[40:41]
	v_cndmask_b32_e64 v2, v2, v8, s[40:41]
	v_pk_mul_f32 v[8:9], v[96:97], v[6:7] op_sel:[0,1] op_sel_hi:[1,0]
	s_nop 0
	v_pk_fma_f32 v[10:11], v[108:109], v[6:7], v[8:9] neg_lo:[0,0,1] neg_hi:[0,0,1]
	v_pk_fma_f32 v[6:7], v[108:109], v[6:7], v[8:9]
	s_nop 0
	v_mov_b32_e32 v11, v7
	v_pk_add_f32 v[2:3], v[2:3], v[10:11]
	s_nop 0
	v_pk_mul_f32 v[6:7], v[96:97], v[2:3]
	s_nop 0
	v_pk_fma_f32 v[8:9], v[108:109], v[2:3], v[6:7] op_sel:[0,0,1] op_sel_hi:[1,1,0] neg_lo:[0,0,1] neg_hi:[0,0,1]
	v_pk_fma_f32 v[2:3], v[108:109], v[2:3], v[6:7] op_sel:[0,0,1] op_sel_hi:[1,1,0]
	s_nop 0
	v_mov_b32_e32 v9, v3
	s_waitcnt lgkmcnt(0)
	v_cndmask_b32_e64 v3, v13, v5, s[40:41]
	v_cndmask_b32_e64 v2, v12, v4, s[40:41]
	v_pk_add_f32 v[2:3], v[2:3], v[8:9]
	v_cndmask_b32_e64 v5, v5, v13, s[40:41]
	v_pk_mul_f32 v[6:7], v[96:97], v[2:3]
	v_cndmask_b32_e64 v4, v4, v12, s[40:41]
	v_pk_fma_f32 v[8:9], v[108:109], v[2:3], v[6:7] op_sel:[0,0,1] op_sel_hi:[1,1,0] neg_lo:[0,0,1] neg_hi:[0,0,1]
	v_pk_fma_f32 v[2:3], v[108:109], v[2:3], v[6:7] op_sel:[0,0,1] op_sel_hi:[1,1,0]
	s_nop 0
	v_mov_b32_e32 v9, v3
	v_pk_add_f32 v[114:115], v[4:5], v[8:9]
	s_cbranch_scc0 .LBB0_424
	s_and_saveexec_b64 s[22:23], s[40:41]
	s_cbranch_execz .LBB0_422
	s_lshl_b32 s4, s30, 6
	s_or_b32 s24, s4, s31
	s_ashr_i32 s25, s24, 31
	s_lshl_b64 s[24:25], s[24:25], 14
	s_add_u32 s4, s14, s24
	s_addc_u32 s25, s16, s25
	s_lshl_b32 s24, s29, 9
	s_add_u32 s24, s4, s24
	s_addc_u32 s25, s25, 0
	v_lshlrev_b32_e32 v2, 3, v86
	global_store_dwordx2 v2, v[116:117], s[24:25]
	global_store_dwordx2 v120, v[114:115], s[24:25] offset:256
	s_branch .LBB0_422
